# fused tiles: row-sum adds packed only deep inside VALU-only runs (scalar pairs within 6 instructions of an MFMA); GEMM K-loop counter/exit test moved into the last MFMA block
# speedup vs baseline: 1.0109x; 1.0001x over previous
.LBB0_367:
	ds_read_b128 v[130:133], v168
	ds_read_b128 v[134:137], v168 offset:1024
	ds_read_b128 v[138:141], v168 offset:2048
	ds_read_b128 v[142:145], v168 offset:3072
	ds_read_b128 v[172:175], v169
	ds_read_b128 v[176:179], v169 offset:1024
	ds_read_b128 v[180:183], v169 offset:2048
	ds_read_b128 v[184:187], v169 offset:3072
	s_add_u32 s36, s34, 0xfffc0080
	s_addc_u32 s37, s35, -1
	s_cmp_eq_u32 s65, 12
	s_cselect_b32 s39, s1, s37
	s_cselect_b32 s38, s25, s36
	s_cselect_b32 s37, s23, s41
	s_cselect_b32 s36, s31, s40
	v_lshl_add_u64 v[166:167], s[34:35], 0, v[158:159]
	s_add_i32 m0, s47, 0xc000
	ds_read_b128 v[188:191], v170
	ds_read_b128 v[192:195], v170 offset:1024
	ds_read_b128 v[196:199], v170 offset:2048
	ds_read_b128 v[200:203], v170 offset:3072
	ds_read_b128 v[204:207], v170 offset:4096
	ds_read_b128 v[208:211], v170 offset:5120
	ds_read_b128 v[212:215], v170 offset:6144
	ds_read_b128 v[216:219], v170 offset:7168
	global_load_lds_dwordx4 v[166:167], off
	v_lshl_add_u64 v[166:167], s[34:35], 0, v[160:161]
	s_add_i32 m0, s47, 0xe000
	s_nop 0
	global_load_lds_dwordx4 v[166:167], off
	s_waitcnt vmcnt(8)
	s_waitcnt lgkmcnt(0)
	s_barrier
	s_setprio 1
	s_waitcnt lgkmcnt(0)
	v_mfma_f32_16x16x32_bf16 v[126:129], v[130:133], v[188:191], v[126:129]
	v_mfma_f32_16x16x32_bf16 v[122:125], v[138:141], v[188:191], v[122:125]
	v_mfma_f32_16x16x32_bf16 v[110:113], v[130:133], v[196:199], v[110:113]
	v_mfma_f32_16x16x32_bf16 v[106:109], v[138:141], v[196:199], v[106:109]
	v_mfma_f32_16x16x32_bf16 v[94:97], v[130:133], v[204:207], v[94:97]
	v_mfma_f32_16x16x32_bf16 v[90:93], v[138:141], v[204:207], v[90:93]
	v_mfma_f32_16x16x32_bf16 v[78:81], v[130:133], v[212:215], v[78:81]
	v_mfma_f32_16x16x32_bf16 v[74:77], v[138:141], v[212:215], v[74:77]
	v_mfma_f32_16x16x32_bf16 v[126:129], v[134:137], v[192:195], v[126:129]
	v_mfma_f32_16x16x32_bf16 v[122:125], v[142:145], v[192:195], v[122:125]
	v_mfma_f32_16x16x32_bf16 v[110:113], v[134:137], v[200:203], v[110:113]
	v_mfma_f32_16x16x32_bf16 v[106:109], v[142:145], v[200:203], v[106:109]
	v_mfma_f32_16x16x32_bf16 v[94:97], v[134:137], v[208:211], v[94:97]
	v_mfma_f32_16x16x32_bf16 v[90:93], v[142:145], v[208:211], v[90:93]
	v_mfma_f32_16x16x32_bf16 v[78:81], v[134:137], v[216:219], v[78:81]
	v_mfma_f32_16x16x32_bf16 v[74:77], v[142:145], v[216:219], v[74:77]
	s_setprio 0
	s_setprio 1
	v_mfma_f32_16x16x32_bf16 v[118:121], v[172:175], v[188:191], v[118:121]
	v_mfma_f32_16x16x32_bf16 v[114:117], v[180:183], v[188:191], v[114:117]
	v_mfma_f32_16x16x32_bf16 v[102:105], v[172:175], v[196:199], v[102:105]
	v_mfma_f32_16x16x32_bf16 v[98:101], v[180:183], v[196:199], v[98:101]
	v_mfma_f32_16x16x32_bf16 v[86:89], v[172:175], v[204:207], v[86:89]
	v_mfma_f32_16x16x32_bf16 v[82:85], v[180:183], v[204:207], v[82:85]
	v_mfma_f32_16x16x32_bf16 v[70:73], v[172:175], v[212:215], v[70:73]
	v_mfma_f32_16x16x32_bf16 v[66:69], v[180:183], v[212:215], v[66:69]
	v_mfma_f32_16x16x32_bf16 v[118:121], v[176:179], v[192:195], v[118:121]
	v_mfma_f32_16x16x32_bf16 v[114:117], v[184:187], v[192:195], v[114:117]
	v_mfma_f32_16x16x32_bf16 v[102:105], v[176:179], v[200:203], v[102:105]
	v_mfma_f32_16x16x32_bf16 v[98:101], v[184:187], v[200:203], v[98:101]
	v_mfma_f32_16x16x32_bf16 v[86:89], v[176:179], v[208:211], v[86:89]
	v_mfma_f32_16x16x32_bf16 v[82:85], v[184:187], v[208:211], v[82:85]
	v_mfma_f32_16x16x32_bf16 v[70:73], v[176:179], v[216:219], v[70:73]
	v_mfma_f32_16x16x32_bf16 v[66:69], v[184:187], v[216:219], v[66:69]
	s_setprio 0
	s_barrier
	s_add_i32 s66, s61, s46
	v_lshl_add_u64 v[166:167], s[36:37], 0, v[148:149]
	s_mov_b32 m0, s66
	ds_read_b128 v[188:191], v170 offset:16384
	ds_read_b128 v[192:195], v170 offset:17408
	ds_read_b128 v[196:199], v170 offset:18432
	ds_read_b128 v[200:203], v170 offset:19456
	ds_read_b128 v[204:207], v170 offset:20480
	ds_read_b128 v[208:211], v170 offset:21504
	ds_read_b128 v[212:215], v170 offset:22528
	ds_read_b128 v[216:219], v170 offset:23552
	global_load_lds_dwordx4 v[166:167], off
	s_add_i32 m0, s66, 0x2000
	s_add_u32 s66, s36, 0x10000
	v_lshl_add_u64 v[220:221], s[36:37], 0, v[152:153]
	s_addc_u32 s67, s37, 0
	s_add_i32 s68, s62, s46
	global_load_lds_dwordx4 v[220:221], off
	v_lshl_add_u64 v[222:223], s[66:67], 0, v[148:149]
	s_mov_b32 m0, s68
	v_lshl_add_u64 v[224:225], s[38:39], 0, v[150:151]
	global_load_lds_dwordx4 v[222:223], off
	v_lshl_add_u64 v[222:223], s[66:67], 0, v[152:153]
	s_add_i32 m0, s68, 0x2000
	s_nop 0
	global_load_lds_dwordx4 v[222:223], off
	v_lshl_add_u64 v[222:223], s[38:39], 0, v[146:147]
	s_mov_b32 m0, s47
	s_nop 0
	global_load_lds_dwordx4 v[222:223], off
	s_mov_b32 m0, s48
	s_nop 0
	global_load_lds_dwordx4 v[224:225], off
	s_waitcnt vmcnt(8)
	s_waitcnt lgkmcnt(0)
	s_barrier
	s_setprio 1
	s_waitcnt lgkmcnt(0)
	v_mfma_f32_16x16x32_bf16 v[62:65], v[130:133], v[188:191], v[62:65]
	v_mfma_f32_16x16x32_bf16 v[58:61], v[138:141], v[188:191], v[58:61]
	v_mfma_f32_16x16x32_bf16 v[46:49], v[130:133], v[196:199], v[46:49]
	v_mfma_f32_16x16x32_bf16 v[42:45], v[138:141], v[196:199], v[42:45]
	v_mfma_f32_16x16x32_bf16 v[30:33], v[130:133], v[204:207], v[30:33]
	v_mfma_f32_16x16x32_bf16 v[26:29], v[138:141], v[204:207], v[26:29]
	v_mfma_f32_16x16x32_bf16 v[14:17], v[130:133], v[212:215], v[14:17]
	v_mfma_f32_16x16x32_bf16 v[10:13], v[138:141], v[212:215], v[10:13]
	v_mfma_f32_16x16x32_bf16 v[62:65], v[134:137], v[192:195], v[62:65]
	v_mfma_f32_16x16x32_bf16 v[58:61], v[142:145], v[192:195], v[58:61]
	v_mfma_f32_16x16x32_bf16 v[46:49], v[134:137], v[200:203], v[46:49]
	v_mfma_f32_16x16x32_bf16 v[42:45], v[142:145], v[200:203], v[42:45]
	v_mfma_f32_16x16x32_bf16 v[30:33], v[134:137], v[208:211], v[30:33]
	v_mfma_f32_16x16x32_bf16 v[26:29], v[142:145], v[208:211], v[26:29]
	v_mfma_f32_16x16x32_bf16 v[14:17], v[134:137], v[216:219], v[14:17]
	v_mfma_f32_16x16x32_bf16 v[10:13], v[142:145], v[216:219], v[10:13]
	s_setprio 0
	s_setprio 1
	v_mfma_f32_16x16x32_bf16 v[54:57], v[172:175], v[188:191], v[54:57]
	v_mfma_f32_16x16x32_bf16 v[50:53], v[180:183], v[188:191], v[50:53]
	v_mfma_f32_16x16x32_bf16 v[38:41], v[172:175], v[196:199], v[38:41]
	v_mfma_f32_16x16x32_bf16 v[34:37], v[180:183], v[196:199], v[34:37]
	v_mfma_f32_16x16x32_bf16 v[22:25], v[172:175], v[204:207], v[22:25]
	v_mfma_f32_16x16x32_bf16 v[18:21], v[180:183], v[204:207], v[18:21]
	v_mfma_f32_16x16x32_bf16 v[6:9], v[172:175], v[212:215], v[6:9]
	v_mfma_f32_16x16x32_bf16 v[2:5], v[180:183], v[212:215], v[2:5]
	v_mfma_f32_16x16x32_bf16 v[54:57], v[176:179], v[192:195], v[54:57]
	v_mfma_f32_16x16x32_bf16 v[50:53], v[184:187], v[192:195], v[50:53]
	v_mfma_f32_16x16x32_bf16 v[38:41], v[176:179], v[200:203], v[38:41]
	v_mfma_f32_16x16x32_bf16 v[34:37], v[184:187], v[200:203], v[34:37]
	v_mfma_f32_16x16x32_bf16 v[22:25], v[176:179], v[208:211], v[22:25]
	v_mfma_f32_16x16x32_bf16 v[18:21], v[184:187], v[208:211], v[18:21]
	v_mfma_f32_16x16x32_bf16 v[6:9], v[176:179], v[216:219], v[6:9]
	v_mfma_f32_16x16x32_bf16 v[2:5], v[184:187], v[216:219], v[2:5]
	s_setprio 0
	s_barrier
	s_add_i32 s66, 0, 0x18000
	s_add_i32 s67, 0, 0x1c000
	v_add_u32_e32 v142, s66, v157
	v_add_u32_e32 v154, s67, v157
	ds_read_b128 v[130:133], v142
	ds_read_b128 v[134:137], v142 offset:1024
	ds_read_b128 v[138:141], v142 offset:2048
	ds_read_b128 v[142:145], v142 offset:3072
	ds_read_b128 v[172:175], v154
	ds_read_b128 v[176:179], v154 offset:1024
	ds_read_b128 v[180:183], v154 offset:2048
	ds_read_b128 v[184:187], v154 offset:3072
	s_add_u32 s38, s38, 0x40000
	s_addc_u32 s39, s39, 0
	s_mov_b32 m0, s49
	v_lshl_add_u64 v[226:227], s[38:39], 0, v[146:147]
	ds_read_b128 v[188:191], v170 offset:32768
	ds_read_b128 v[192:195], v170 offset:33792
	ds_read_b128 v[196:199], v170 offset:34816
	ds_read_b128 v[200:203], v170 offset:35840
	ds_read_b128 v[204:207], v170 offset:36864
	ds_read_b128 v[208:211], v170 offset:37888
	ds_read_b128 v[212:215], v170 offset:38912
	ds_read_b128 v[216:219], v170 offset:39936
	global_load_lds_dwordx4 v[226:227], off
	v_lshl_add_u64 v[226:227], s[38:39], 0, v[150:151]
	s_mov_b32 m0, s50
	s_nop 0
	global_load_lds_dwordx4 v[226:227], off
	s_waitcnt vmcnt(8)
	s_waitcnt lgkmcnt(0)
	s_barrier
	s_setprio 1
	s_waitcnt lgkmcnt(0)
	v_mfma_f32_16x16x32_bf16 v[126:129], v[130:133], v[188:191], v[126:129]
	v_mfma_f32_16x16x32_bf16 v[122:125], v[138:141], v[188:191], v[122:125]
	v_mfma_f32_16x16x32_bf16 v[110:113], v[130:133], v[196:199], v[110:113]
	v_mfma_f32_16x16x32_bf16 v[106:109], v[138:141], v[196:199], v[106:109]
	v_mfma_f32_16x16x32_bf16 v[94:97], v[130:133], v[204:207], v[94:97]
	v_mfma_f32_16x16x32_bf16 v[90:93], v[138:141], v[204:207], v[90:93]
	v_mfma_f32_16x16x32_bf16 v[78:81], v[130:133], v[212:215], v[78:81]
	v_mfma_f32_16x16x32_bf16 v[74:77], v[138:141], v[212:215], v[74:77]
	v_mfma_f32_16x16x32_bf16 v[126:129], v[134:137], v[192:195], v[126:129]
	v_mfma_f32_16x16x32_bf16 v[122:125], v[142:145], v[192:195], v[122:125]
	v_mfma_f32_16x16x32_bf16 v[110:113], v[134:137], v[200:203], v[110:113]
	v_mfma_f32_16x16x32_bf16 v[106:109], v[142:145], v[200:203], v[106:109]
	v_mfma_f32_16x16x32_bf16 v[94:97], v[134:137], v[208:211], v[94:97]
	v_mfma_f32_16x16x32_bf16 v[90:93], v[142:145], v[208:211], v[90:93]
	v_mfma_f32_16x16x32_bf16 v[78:81], v[134:137], v[216:219], v[78:81]
	v_mfma_f32_16x16x32_bf16 v[74:77], v[142:145], v[216:219], v[74:77]
	s_setprio 0
	s_setprio 1
	v_mfma_f32_16x16x32_bf16 v[118:121], v[172:175], v[188:191], v[118:121]
	v_mfma_f32_16x16x32_bf16 v[114:117], v[180:183], v[188:191], v[114:117]
	v_mfma_f32_16x16x32_bf16 v[102:105], v[172:175], v[196:199], v[102:105]
	v_mfma_f32_16x16x32_bf16 v[98:101], v[180:183], v[196:199], v[98:101]
	v_mfma_f32_16x16x32_bf16 v[86:89], v[172:175], v[204:207], v[86:89]
	v_mfma_f32_16x16x32_bf16 v[82:85], v[180:183], v[204:207], v[82:85]
	v_mfma_f32_16x16x32_bf16 v[70:73], v[172:175], v[212:215], v[70:73]
	v_mfma_f32_16x16x32_bf16 v[66:69], v[180:183], v[212:215], v[66:69]
	v_mfma_f32_16x16x32_bf16 v[118:121], v[176:179], v[192:195], v[118:121]
	v_mfma_f32_16x16x32_bf16 v[114:117], v[184:187], v[192:195], v[114:117]
	v_mfma_f32_16x16x32_bf16 v[102:105], v[176:179], v[200:203], v[102:105]
	v_mfma_f32_16x16x32_bf16 v[98:101], v[184:187], v[200:203], v[98:101]
	v_mfma_f32_16x16x32_bf16 v[86:89], v[176:179], v[208:211], v[86:89]
	v_mfma_f32_16x16x32_bf16 v[82:85], v[184:187], v[208:211], v[82:85]
	v_mfma_f32_16x16x32_bf16 v[70:73], v[176:179], v[216:219], v[70:73]
	v_mfma_f32_16x16x32_bf16 v[66:69], v[184:187], v[216:219], v[66:69]
	s_setprio 0
	s_barrier
	s_add_i32 s38, s66, s46
	v_lshl_add_u64 v[166:167], v[166:167], 0, s[18:19]
	s_mov_b32 m0, s38
	ds_read_b128 v[188:191], v170 offset:49152
	ds_read_b128 v[192:195], v170 offset:50176
	ds_read_b128 v[196:199], v170 offset:51200
	ds_read_b128 v[200:203], v170 offset:52224
	ds_read_b128 v[204:207], v170 offset:53248
	ds_read_b128 v[208:211], v170 offset:54272
	ds_read_b128 v[212:215], v170 offset:55296
	ds_read_b128 v[216:219], v170 offset:56320
	global_load_lds_dwordx4 v[166:167], off
	s_add_i32 m0, s38, 0x2000
	s_add_u32 s36, s36, 0x10080
	v_lshl_add_u64 v[166:167], v[220:221], 0, s[18:19]
	s_addc_u32 s37, s37, 0
	s_add_i32 s38, s67, s46
	global_load_lds_dwordx4 v[166:167], off
	v_lshl_add_u64 v[166:167], s[36:37], 0, v[148:149]
	s_mov_b32 m0, s38
	s_nop 0
	global_load_lds_dwordx4 v[166:167], off
	v_lshl_add_u64 v[166:167], s[36:37], 0, v[152:153]
	s_add_i32 m0, s38, 0x2000
	s_nop 0
	global_load_lds_dwordx4 v[166:167], off
	v_lshl_add_u64 v[166:167], v[222:223], 0, s[18:19]
	s_mov_b32 m0, s56
	s_nop 0
	global_load_lds_dwordx4 v[166:167], off
	v_lshl_add_u64 v[166:167], v[224:225], 0, s[18:19]
	s_mov_b32 m0, s57
	s_nop 0
	global_load_lds_dwordx4 v[166:167], off
	s_waitcnt vmcnt(8)
	s_waitcnt lgkmcnt(0)
	s_barrier
	s_setprio 1
	s_waitcnt lgkmcnt(0)
	v_mfma_f32_16x16x32_bf16 v[62:65], v[130:133], v[188:191], v[62:65]
	v_mfma_f32_16x16x32_bf16 v[58:61], v[138:141], v[188:191], v[58:61]
	v_mfma_f32_16x16x32_bf16 v[46:49], v[130:133], v[196:199], v[46:49]
	v_mfma_f32_16x16x32_bf16 v[42:45], v[138:141], v[196:199], v[42:45]
	v_mfma_f32_16x16x32_bf16 v[30:33], v[130:133], v[204:207], v[30:33]
	v_mfma_f32_16x16x32_bf16 v[26:29], v[138:141], v[204:207], v[26:29]
	v_mfma_f32_16x16x32_bf16 v[14:17], v[130:133], v[212:215], v[14:17]
	v_mfma_f32_16x16x32_bf16 v[10:13], v[138:141], v[212:215], v[10:13]
	v_mfma_f32_16x16x32_bf16 v[62:65], v[134:137], v[192:195], v[62:65]
	v_mfma_f32_16x16x32_bf16 v[58:61], v[142:145], v[192:195], v[58:61]
	v_mfma_f32_16x16x32_bf16 v[46:49], v[134:137], v[200:203], v[46:49]
	v_mfma_f32_16x16x32_bf16 v[42:45], v[142:145], v[200:203], v[42:45]
	v_mfma_f32_16x16x32_bf16 v[30:33], v[134:137], v[208:211], v[30:33]
	v_mfma_f32_16x16x32_bf16 v[26:29], v[142:145], v[208:211], v[26:29]
	v_mfma_f32_16x16x32_bf16 v[14:17], v[134:137], v[216:219], v[14:17]
	v_mfma_f32_16x16x32_bf16 v[10:13], v[142:145], v[216:219], v[10:13]
	s_setprio 0
	s_setprio 1
	v_mfma_f32_16x16x32_bf16 v[54:57], v[172:175], v[188:191], v[54:57]
	v_mfma_f32_16x16x32_bf16 v[50:53], v[180:183], v[188:191], v[50:53]
	v_mfma_f32_16x16x32_bf16 v[38:41], v[172:175], v[196:199], v[38:41]
	v_mfma_f32_16x16x32_bf16 v[34:37], v[180:183], v[196:199], v[34:37]
	v_mfma_f32_16x16x32_bf16 v[22:25], v[172:175], v[204:207], v[22:25]
	s_add_i32 s65, s65, 2
	v_mfma_f32_16x16x32_bf16 v[18:21], v[180:183], v[204:207], v[18:21]
	v_mfma_f32_16x16x32_bf16 v[6:9], v[172:175], v[212:215], v[6:9]
	s_add_u32 s34, s34, 0x100
	s_addc_u32 s35, s35, 0
	v_mfma_f32_16x16x32_bf16 v[2:5], v[180:183], v[212:215], v[2:5]
	v_mfma_f32_16x16x32_bf16 v[54:57], v[176:179], v[192:195], v[54:57]
	s_add_u32 s40, s40, 0x100
	s_addc_u32 s41, s41, 0
	v_mfma_f32_16x16x32_bf16 v[50:53], v[184:187], v[192:195], v[50:53]
	v_mfma_f32_16x16x32_bf16 v[38:41], v[176:179], v[200:203], v[38:41]
	s_cmp_gt_u32 s65, 13
	v_mfma_f32_16x16x32_bf16 v[34:37], v[184:187], v[200:203], v[34:37]
	v_mfma_f32_16x16x32_bf16 v[22:25], v[176:179], v[208:211], v[22:25]
	v_mfma_f32_16x16x32_bf16 v[18:21], v[184:187], v[208:211], v[18:21]
	v_mfma_f32_16x16x32_bf16 v[6:9], v[176:179], v[216:219], v[6:9]
	v_mfma_f32_16x16x32_bf16 v[2:5], v[184:187], v[216:219], v[2:5]
	s_setprio 0
	s_barrier
	s_cbranch_scc0 .LBB0_367
	s_and_b64 vcc, exec, s[20:21]
	s_cbranch_vccz .LBB0_370
	s_barrier

.LBB0_658:
	s_and_b64 vcc, exec, s[0:1]
	s_cbranch_vccz .LBB0_653
	s_lshl_b32 s0, s76, 14
	s_or_b32 s76, s0, s21
	s_lshl_b32 s77, s77, 6
	s_add_i32 s78, s77, 63
	s_cmp_gt_i32 s78, s72
	s_cbranch_scc1 .Lflt_no
	s_cmp_lt_i32 s77, s71
	s_cbranch_scc1 .Lflt_no
	s_sub_i32 s0, s33, s78
	s_cmpk_gt_i32 s0, 0x7f
	s_cselect_b64 s[0:1], -1, 0
	s_or_b64 s[0:1], s[0:1], s[30:31]
	s_and_b64 vcc, exec, s[0:1]
	s_cbranch_vccz .Lflt_no
	v_add_u32_e32 v3, s76, v198
	ds_read_b128 v[4:7], v3
	v_add_u32_e32 v16, s76, v206
	ds_read_b128 v[8:11], v16
	v_add_u32_e32 v17, s76, v207
	ds_read_b128 v[12:15], v17
	v_add_u32_e32 v238, s76, v208
	ds_read_b128 v[214:217], v238
	ds_read_b128 v[234:237], v3 offset:4096
	ds_read_b128 v[244:247], v16 offset:4096
	ds_read_b128 v[248:251], v17 offset:4096
	ds_read_b128 v[252:255], v238 offset:4096
	s_setprio 1
	s_waitcnt lgkmcnt(7)
	v_mfma_f32_32x32x16_bf16 v[118:133], v[4:7], v[134:137], v[86:101]
	s_waitcnt lgkmcnt(6)
	v_mfma_f32_32x32x16_bf16 v[118:133], v[8:11], v[138:141], v[118:133]
	s_waitcnt lgkmcnt(5)
	v_mfma_f32_32x32x16_bf16 v[118:133], v[12:15], v[142:145], v[118:133]
	s_waitcnt lgkmcnt(4)
	v_mfma_f32_32x32x16_bf16 v[118:133], v[214:217], v[150:153], v[118:133]
	s_add_i32 s0, s76, 0x2000
	v_mfma_f32_32x32x16_bf16 v[102:117], v[4:7], v[146:149], v[86:101]
	v_add_u32_e32 v3, s0, v200
	ds_read_b64_tr_b16 v[4:5], v3 offset:0
	ds_read_b64_tr_b16 v[6:7], v3 offset:1024
	v_mfma_f32_32x32x16_bf16 v[102:117], v[8:11], v[154:157], v[102:117]
	ds_read_b64_tr_b16 v[8:9], v3 offset:2048
	ds_read_b64_tr_b16 v[10:11], v3 offset:3072
	s_nop 4
	v_exp_f32_e32 v118, v118
	v_exp_f32_e32 v119, v119
	v_exp_f32_e32 v120, v120
	v_mfma_f32_32x32x16_bf16 v[102:117], v[12:15], v[158:161], v[102:117]
	v_add_u32_e32 v3, s0, v201
	ds_read_b64_tr_b16 v[12:13], v3 offset:0
	ds_read_b64_tr_b16 v[14:15], v3 offset:1024
	v_exp_f32_e32 v121, v121
	v_exp_f32_e32 v122, v122
	v_exp_f32_e32 v123, v123
	v_mfma_f32_32x32x16_bf16 v[102:117], v[214:217], v[162:165], v[102:117]
	ds_read_b64_tr_b16 v[214:215], v3 offset:2048
	ds_read_b64_tr_b16 v[216:217], v3 offset:3072
	v_exp_f32_e32 v124, v124
	v_exp_f32_e32 v125, v125
	v_exp_f32_e32 v126, v126
	s_waitcnt lgkmcnt(8)
	v_mfma_f32_32x32x16_bf16 v[218:233], v[234:237], v[134:137], v[86:101]
	v_exp_f32_e32 v127, v127
	v_exp_f32_e32 v128, v128
	v_exp_f32_e32 v129, v129
	v_mfma_f32_32x32x16_bf16 v[218:233], v[244:247], v[138:141], v[218:233]
	v_exp_f32_e32 v130, v130
	v_exp_f32_e32 v131, v131
	v_exp_f32_e32 v132, v132
	v_mfma_f32_32x32x16_bf16 v[218:233], v[248:251], v[142:145], v[218:233]
	v_exp_f32_e32 v133, v133
	v_add_f32_e32 v16, v118, v120
	v_add_f32_e32 v17, v119, v121
	v_add_f32_e32 v16, v16, v122
	v_add_f32_e32 v17, v17, v123
	v_add_f32_e32 v16, v16, v124
	v_add_f32_e32 v17, v17, v125
	v_cvt_pk_bf16_f32 v118, v118, v119
	v_cvt_pk_bf16_f32 v119, v120, v121
	v_cvt_pk_bf16_f32 v120, v122, v123
	v_mfma_f32_32x32x16_bf16 v[218:233], v[252:255], v[150:153], v[218:233]
	v_cvt_pk_bf16_f32 v121, v124, v125
	v_cvt_pk_bf16_f32 v122, v126, v127
	v_cvt_pk_bf16_f32 v123, v128, v129
	v_cvt_pk_bf16_f32 v124, v130, v131
	v_cvt_pk_bf16_f32 v125, v132, v133
	v_add_f32_e32 v16, v16, v126
	v_add_f32_e32 v17, v17, v127
	v_add_f32_e32 v16, v16, v128
	v_add_f32_e32 v17, v17, v129
	v_add_f32_e32 v16, v16, v130
	v_add_f32_e32 v17, v17, v131
	v_add_f32_e32 v16, v16, v132
	v_add_f32_e32 v17, v17, v133
	s_waitcnt lgkmcnt(0)
	v_mfma_f32_32x32x16_bf16 v[20:35], v[4:7], v[118:121], v[20:35]
	v_exp_f32_e32 v102, v102
	v_exp_f32_e32 v103, v103
	v_exp_f32_e32 v104, v104
	v_mfma_f32_32x32x16_bf16 v[36:51], v[12:15], v[118:121], v[36:51]
	v_exp_f32_e32 v105, v105
	v_exp_f32_e32 v106, v106
	v_exp_f32_e32 v107, v107
	v_mfma_f32_32x32x16_bf16 v[20:35], v[8:11], v[122:125], v[20:35]
	v_exp_f32_e32 v108, v108
	v_exp_f32_e32 v109, v109
	v_exp_f32_e32 v110, v110
	v_mfma_f32_32x32x16_bf16 v[36:51], v[214:217], v[122:125], v[36:51]
	v_exp_f32_e32 v111, v111
	v_exp_f32_e32 v112, v112
	v_exp_f32_e32 v113, v113
	s_add_i32 s0, s76, 0x3000
	v_mfma_f32_32x32x16_bf16 v[118:133], v[234:237], v[146:149], v[86:101]
	v_add_u32_e32 v3, s0, v200
	ds_read_b64_tr_b16 v[234:235], v3 offset:0
	ds_read_b64_tr_b16 v[236:237], v3 offset:1024
	v_exp_f32_e32 v114, v114
	v_exp_f32_e32 v115, v115
	v_exp_f32_e32 v116, v116
	v_mfma_f32_32x32x16_bf16 v[118:133], v[244:247], v[154:157], v[118:133]
	ds_read_b64_tr_b16 v[244:245], v3 offset:2048
	ds_read_b64_tr_b16 v[246:247], v3 offset:3072
	v_exp_f32_e32 v117, v117
	v_add_f32_e32 v238, v102, v104
	v_add_f32_e32 v239, v103, v105
	v_add_f32_e32 v238, v238, v106
	v_add_f32_e32 v239, v239, v107
	v_add_f32_e32 v238, v238, v108
	v_add_f32_e32 v239, v239, v109
	v_cvt_pk_bf16_f32 v102, v102, v103
	v_cvt_pk_bf16_f32 v103, v104, v105
	v_mfma_f32_32x32x16_bf16 v[118:133], v[248:251], v[158:161], v[118:133]
	v_add_u32_e32 v3, s0, v201
	ds_read_b64_tr_b16 v[248:249], v3 offset:0
	ds_read_b64_tr_b16 v[250:251], v3 offset:1024
	v_cvt_pk_bf16_f32 v104, v106, v107
	v_cvt_pk_bf16_f32 v105, v108, v109
	v_cvt_pk_bf16_f32 v106, v110, v111
	v_cvt_pk_bf16_f32 v107, v112, v113
	v_cvt_pk_bf16_f32 v108, v114, v115
	v_cvt_pk_bf16_f32 v109, v116, v117
	v_mfma_f32_32x32x16_bf16 v[118:133], v[252:255], v[162:165], v[118:133]
	ds_read_b64_tr_b16 v[252:253], v3 offset:2048
	ds_read_b64_tr_b16 v[254:255], v3 offset:3072
	v_add_f32_e32 v238, v238, v110
	v_add_f32_e32 v239, v239, v111
	v_add_f32_e32 v238, v238, v112
	v_add_f32_e32 v239, v239, v113
	v_add_f32_e32 v238, v238, v114
	v_add_f32_e32 v239, v239, v115
	v_add_f32_e32 v238, v238, v116
	v_add_f32_e32 v239, v239, v117
	v_mfma_f32_32x32x16_bf16 v[68:83], v[4:7], v[102:105], v[68:83]
	v_exp_f32_e32 v218, v218
	v_exp_f32_e32 v219, v219
	v_exp_f32_e32 v220, v220
	v_mfma_f32_32x32x16_bf16 v[52:67], v[12:15], v[102:105], v[52:67]
	v_exp_f32_e32 v221, v221
	v_exp_f32_e32 v222, v222
	v_exp_f32_e32 v223, v223
	v_mfma_f32_32x32x16_bf16 v[68:83], v[8:11], v[106:109], v[68:83]
	v_exp_f32_e32 v224, v224
	v_exp_f32_e32 v225, v225
	v_exp_f32_e32 v226, v226
	v_mfma_f32_32x32x16_bf16 v[52:67], v[214:217], v[106:109], v[52:67]
	v_exp_f32_e32 v227, v227
	v_exp_f32_e32 v228, v228
	v_exp_f32_e32 v229, v229
	v_exp_f32_e32 v230, v230
	v_exp_f32_e32 v231, v231
	v_exp_f32_e32 v232, v232
	v_exp_f32_e32 v233, v233
	v_pk_add_f32 v[16:17], v[16:17], v[218:219]
	v_pk_add_f32 v[16:17], v[16:17], v[220:221]
	v_pk_add_f32 v[16:17], v[16:17], v[222:223]
	v_pk_add_f32 v[16:17], v[16:17], v[224:225]
	v_cvt_pk_bf16_f32 v218, v218, v219
	v_cvt_pk_bf16_f32 v219, v220, v221
	v_cvt_pk_bf16_f32 v220, v222, v223
	v_cvt_pk_bf16_f32 v221, v224, v225
	v_cvt_pk_bf16_f32 v222, v226, v227
	v_cvt_pk_bf16_f32 v223, v228, v229
	v_cvt_pk_bf16_f32 v224, v230, v231
	v_cvt_pk_bf16_f32 v225, v232, v233
	s_waitcnt lgkmcnt(0)
	v_mfma_f32_32x32x16_bf16 v[20:35], v[234:237], v[218:221], v[20:35]
	v_exp_f32_e32 v118, v118
	v_exp_f32_e32 v119, v119
	v_exp_f32_e32 v120, v120
	v_mfma_f32_32x32x16_bf16 v[36:51], v[248:251], v[218:221], v[36:51]
	v_exp_f32_e32 v121, v121
	v_exp_f32_e32 v122, v122
	v_exp_f32_e32 v123, v123
	v_mfma_f32_32x32x16_bf16 v[20:35], v[244:247], v[222:225], v[20:35]
	v_exp_f32_e32 v124, v124
	v_exp_f32_e32 v125, v125
	v_exp_f32_e32 v126, v126
	v_mfma_f32_32x32x16_bf16 v[36:51], v[252:255], v[222:225], v[36:51]
	v_exp_f32_e32 v127, v127
	v_exp_f32_e32 v128, v128
	v_exp_f32_e32 v129, v129
	v_exp_f32_e32 v130, v130
	v_exp_f32_e32 v131, v131
	v_exp_f32_e32 v132, v132
	v_exp_f32_e32 v133, v133
	v_pk_add_f32 v[238:239], v[238:239], v[118:119]
	v_pk_add_f32 v[238:239], v[238:239], v[120:121]
	v_pk_add_f32 v[238:239], v[238:239], v[122:123]
	v_pk_add_f32 v[238:239], v[238:239], v[124:125]
	v_cvt_pk_bf16_f32 v118, v118, v119
	v_cvt_pk_bf16_f32 v119, v120, v121
	v_cvt_pk_bf16_f32 v120, v122, v123
	v_cvt_pk_bf16_f32 v121, v124, v125
	v_cvt_pk_bf16_f32 v122, v126, v127
	v_cvt_pk_bf16_f32 v123, v128, v129
	v_cvt_pk_bf16_f32 v124, v130, v131
	v_cvt_pk_bf16_f32 v125, v132, v133
	v_mfma_f32_32x32x16_bf16 v[68:83], v[234:237], v[118:121], v[68:83]
	v_add_f32_e32 v16, v16, v226
	v_add_f32_e32 v17, v17, v227
	v_add_f32_e32 v16, v16, v228
	v_add_f32_e32 v17, v17, v229
	v_mfma_f32_32x32x16_bf16 v[52:67], v[248:251], v[118:121], v[52:67]
	v_add_f32_e32 v16, v16, v230
	v_add_f32_e32 v17, v17, v231
	v_add_f32_e32 v16, v16, v232
	v_add_f32_e32 v17, v17, v233
	v_mfma_f32_32x32x16_bf16 v[68:83], v[244:247], v[122:125], v[68:83]
	v_add_f32_e32 v238, v238, v126
	v_add_f32_e32 v239, v239, v127
	v_add_f32_e32 v238, v238, v128
	v_add_f32_e32 v239, v239, v129
	v_mfma_f32_32x32x16_bf16 v[52:67], v[252:255], v[122:125], v[52:67]
	v_add_f32_e32 v238, v238, v130
	v_add_f32_e32 v239, v239, v131
	v_add_f32_e32 v238, v238, v132
	v_add_f32_e32 v239, v239, v133
	s_setprio 0
	v_add_f32_e32 v16, v16, v17
	v_add_f32_e32 v238, v238, v239
	v_add_f32_e32 v180, v180, v16
	v_add_f32_e32 v181, v181, v238
	s_branch .LBB0_653

.Lfg0_nomask:
	s_nop 1
	v_exp_f32_e32 v118, v118
	v_exp_f32_e32 v119, v119
	v_exp_f32_e32 v120, v120
	v_exp_f32_e32 v121, v121
	v_exp_f32_e32 v122, v122
	v_exp_f32_e32 v123, v123
	v_exp_f32_e32 v124, v124
	v_exp_f32_e32 v125, v125
	v_exp_f32_e32 v126, v126
	v_exp_f32_e32 v127, v127
	v_exp_f32_e32 v128, v128
	v_exp_f32_e32 v129, v129
	v_exp_f32_e32 v130, v130
	v_exp_f32_e32 v131, v131
	v_exp_f32_e32 v132, v132
	v_exp_f32_e32 v133, v133
	v_pk_add_f32 v[16:17], v[118:119], v[120:121]
	v_pk_add_f32 v[16:17], v[16:17], v[122:123]
	v_pk_add_f32 v[16:17], v[16:17], v[124:125]
	v_cvt_pk_bf16_f32 v118, v118, v119
	v_cvt_pk_bf16_f32 v119, v120, v121
	v_cvt_pk_bf16_f32 v120, v122, v123
	v_cvt_pk_bf16_f32 v121, v124, v125
	v_cvt_pk_bf16_f32 v122, v126, v127
	v_cvt_pk_bf16_f32 v123, v128, v129
	v_cvt_pk_bf16_f32 v124, v130, v131
	v_cvt_pk_bf16_f32 v125, v132, v133
	v_add_f32_e32 v16, v16, v126
	v_add_f32_e32 v17, v17, v127
	v_add_f32_e32 v16, v16, v128
	v_add_f32_e32 v17, v17, v129
	v_add_f32_e32 v16, v16, v130
	v_add_f32_e32 v17, v17, v131
	v_add_f32_e32 v16, v16, v132
	v_add_f32_e32 v17, v17, v133
	s_waitcnt lgkmcnt(0)
	v_mfma_f32_32x32x16_bf16 v[20:35], v[234:237], v[118:121], v[20:35]
	v_exp_f32_e32 v102, v102
	v_exp_f32_e32 v103, v103
	v_exp_f32_e32 v104, v104
	v_mfma_f32_32x32x16_bf16 v[36:51], v[248:251], v[118:121], v[36:51]
	v_exp_f32_e32 v105, v105
	v_exp_f32_e32 v106, v106
	v_exp_f32_e32 v107, v107
	v_mfma_f32_32x32x16_bf16 v[20:35], v[244:247], v[122:125], v[20:35]
	v_exp_f32_e32 v108, v108
	v_exp_f32_e32 v109, v109
	v_exp_f32_e32 v110, v110
	v_mfma_f32_32x32x16_bf16 v[36:51], v[252:255], v[122:125], v[36:51]
	v_exp_f32_e32 v111, v111
	v_exp_f32_e32 v112, v112
	v_exp_f32_e32 v113, v113
	v_exp_f32_e32 v114, v114
	v_exp_f32_e32 v115, v115
	v_exp_f32_e32 v116, v116
	v_exp_f32_e32 v117, v117
	v_pk_add_f32 v[238:239], v[102:103], v[104:105]
	v_pk_add_f32 v[238:239], v[238:239], v[106:107]
	v_pk_add_f32 v[238:239], v[238:239], v[108:109]
	v_cvt_pk_bf16_f32 v102, v102, v103
	v_cvt_pk_bf16_f32 v103, v104, v105
	v_cvt_pk_bf16_f32 v104, v106, v107
	v_cvt_pk_bf16_f32 v105, v108, v109
	v_cvt_pk_bf16_f32 v106, v110, v111
	v_cvt_pk_bf16_f32 v107, v112, v113
	v_cvt_pk_bf16_f32 v108, v114, v115
	v_cvt_pk_bf16_f32 v109, v116, v117
	v_mfma_f32_32x32x16_bf16 v[68:83], v[234:237], v[102:105], v[68:83]
	v_add_f32_e32 v238, v238, v110
	v_add_f32_e32 v239, v239, v111
	v_add_f32_e32 v238, v238, v112
	v_add_f32_e32 v239, v239, v113
	v_mfma_f32_32x32x16_bf16 v[52:67], v[248:251], v[102:105], v[52:67]
	v_add_f32_e32 v238, v238, v114
	v_add_f32_e32 v239, v239, v115
	v_add_f32_e32 v238, v238, v116
	v_add_f32_e32 v239, v239, v117
	v_mfma_f32_32x32x16_bf16 v[68:83], v[244:247], v[106:109], v[68:83]
	v_add_f32_e32 v16, v16, v17
	v_mfma_f32_32x32x16_bf16 v[52:67], v[252:255], v[106:109], v[52:67]
	v_add_f32_e32 v180, v180, v16
	s_setprio 0
	v_add_f32_e32 v238, v238, v239
	v_add_f32_e32 v181, v181, v238

.Lfg1_nomask:
	s_nop 1
	v_exp_f32_e32 v118, v118
	v_exp_f32_e32 v119, v119
	v_exp_f32_e32 v120, v120
	v_exp_f32_e32 v121, v121
	v_exp_f32_e32 v122, v122
	v_exp_f32_e32 v123, v123
	v_exp_f32_e32 v124, v124
	v_exp_f32_e32 v125, v125
	v_exp_f32_e32 v126, v126
	v_exp_f32_e32 v127, v127
	v_exp_f32_e32 v128, v128
	v_exp_f32_e32 v129, v129
	v_exp_f32_e32 v130, v130
	v_exp_f32_e32 v131, v131
	v_exp_f32_e32 v132, v132
	v_exp_f32_e32 v133, v133
	v_pk_add_f32 v[16:17], v[118:119], v[120:121]
	v_pk_add_f32 v[16:17], v[16:17], v[122:123]
	v_pk_add_f32 v[16:17], v[16:17], v[124:125]
	v_cvt_pk_bf16_f32 v118, v118, v119
	v_cvt_pk_bf16_f32 v119, v120, v121
	v_cvt_pk_bf16_f32 v120, v122, v123
	v_cvt_pk_bf16_f32 v121, v124, v125
	v_cvt_pk_bf16_f32 v122, v126, v127
	v_cvt_pk_bf16_f32 v123, v128, v129
	v_cvt_pk_bf16_f32 v124, v130, v131
	v_cvt_pk_bf16_f32 v125, v132, v133
	v_add_f32_e32 v16, v16, v126
	v_add_f32_e32 v17, v17, v127
	v_add_f32_e32 v16, v16, v128
	v_add_f32_e32 v17, v17, v129
	v_add_f32_e32 v16, v16, v130
	v_add_f32_e32 v17, v17, v131
	v_add_f32_e32 v16, v16, v132
	v_add_f32_e32 v17, v17, v133
	s_waitcnt lgkmcnt(0)
	v_mfma_f32_32x32x16_bf16 v[20:35], v[234:237], v[118:121], v[20:35]
	v_exp_f32_e32 v102, v102
	v_exp_f32_e32 v103, v103
	v_exp_f32_e32 v104, v104
	v_mfma_f32_32x32x16_bf16 v[36:51], v[248:251], v[118:121], v[36:51]
	v_exp_f32_e32 v105, v105
	v_exp_f32_e32 v106, v106
	v_exp_f32_e32 v107, v107
	v_mfma_f32_32x32x16_bf16 v[20:35], v[244:247], v[122:125], v[20:35]
	v_exp_f32_e32 v108, v108
	v_exp_f32_e32 v109, v109
	v_exp_f32_e32 v110, v110
	v_mfma_f32_32x32x16_bf16 v[36:51], v[252:255], v[122:125], v[36:51]
	v_exp_f32_e32 v111, v111
	v_exp_f32_e32 v112, v112
	v_exp_f32_e32 v113, v113
	v_exp_f32_e32 v114, v114
	v_exp_f32_e32 v115, v115
	v_exp_f32_e32 v116, v116
	v_exp_f32_e32 v117, v117
	v_pk_add_f32 v[238:239], v[102:103], v[104:105]
	v_pk_add_f32 v[238:239], v[238:239], v[106:107]
	v_pk_add_f32 v[238:239], v[238:239], v[108:109]
	v_cvt_pk_bf16_f32 v102, v102, v103
	v_cvt_pk_bf16_f32 v103, v104, v105
	v_cvt_pk_bf16_f32 v104, v106, v107
	v_cvt_pk_bf16_f32 v105, v108, v109
	v_cvt_pk_bf16_f32 v106, v110, v111
	v_cvt_pk_bf16_f32 v107, v112, v113
	v_cvt_pk_bf16_f32 v108, v114, v115
	v_cvt_pk_bf16_f32 v109, v116, v117
	v_mfma_f32_32x32x16_bf16 v[68:83], v[234:237], v[102:105], v[68:83]
	v_add_f32_e32 v238, v238, v110
	v_add_f32_e32 v239, v239, v111
	v_add_f32_e32 v238, v238, v112
	v_add_f32_e32 v239, v239, v113
	v_mfma_f32_32x32x16_bf16 v[52:67], v[248:251], v[102:105], v[52:67]
	v_add_f32_e32 v238, v238, v114
	v_add_f32_e32 v239, v239, v115
	v_add_f32_e32 v238, v238, v116
	v_add_f32_e32 v239, v239, v117
	v_mfma_f32_32x32x16_bf16 v[68:83], v[244:247], v[106:109], v[68:83]
	v_add_f32_e32 v16, v16, v17
	v_mfma_f32_32x32x16_bf16 v[52:67], v[252:255], v[106:109], v[52:67]
	v_add_f32_e32 v180, v180, v16
	s_setprio 0
	v_add_f32_e32 v238, v238, v239
	v_add_f32_e32 v181, v181, v238
	s_branch .LBB0_653

.LBB0_766:
	ds_read_b128 v[128:131], v163
	ds_read_b128 v[132:135], v163 offset:1024
	ds_read_b128 v[136:139], v163 offset:2048
	ds_read_b128 v[140:143], v163 offset:3072
	ds_read_b128 v[156:159], v164
	ds_read_b128 v[166:169], v164 offset:1024
	ds_read_b128 v[170:173], v164 offset:2048
	ds_read_b128 v[174:177], v164 offset:3072
	s_add_u32 s38, s36, 0xfffc0080
	s_addc_u32 s39, s37, -1
	s_cmp_eq_u32 s63, 12
	s_cselect_b32 s41, s27, s39
	s_cselect_b32 s40, s59, s38
	s_cselect_b32 s39, s25, s62
	s_cselect_b32 s38, s60, s61
	v_lshl_add_u64 v[210:211], s[36:37], 0, v[148:149]
	s_add_i32 m0, s35, 0xc000
	ds_read_b128 v[178:181], v165
	ds_read_b128 v[182:185], v165 offset:1024
	ds_read_b128 v[186:189], v165 offset:2048
	ds_read_b128 v[190:193], v165 offset:3072
	ds_read_b128 v[194:197], v165 offset:4096
	ds_read_b128 v[198:201], v165 offset:5120
	ds_read_b128 v[202:205], v165 offset:6144
	ds_read_b128 v[206:209], v165 offset:7168
	global_load_lds_dwordx4 v[210:211], off
	v_lshl_add_u64 v[210:211], s[36:37], 0, v[150:151]
	s_add_i32 m0, s35, 0xe000
	s_nop 0
	global_load_lds_dwordx4 v[210:211], off
	s_waitcnt vmcnt(8)
	s_waitcnt lgkmcnt(0)
	s_barrier
	s_setprio 1
	s_waitcnt lgkmcnt(0)
	v_mfma_f32_16x16x32_bf16 v[124:127], v[128:131], v[178:181], v[124:127]
	v_mfma_f32_16x16x32_bf16 v[120:123], v[136:139], v[178:181], v[120:123]
	v_mfma_f32_16x16x32_bf16 v[116:119], v[128:131], v[186:189], v[116:119]
	v_mfma_f32_16x16x32_bf16 v[108:111], v[136:139], v[186:189], v[108:111]
	v_mfma_f32_16x16x32_bf16 v[96:99], v[128:131], v[194:197], v[96:99]
	v_mfma_f32_16x16x32_bf16 v[88:91], v[136:139], v[194:197], v[88:91]
	v_mfma_f32_16x16x32_bf16 v[84:87], v[128:131], v[202:205], v[84:87]
	v_mfma_f32_16x16x32_bf16 v[76:79], v[136:139], v[202:205], v[76:79]
	v_mfma_f32_16x16x32_bf16 v[124:127], v[132:135], v[182:185], v[124:127]
	v_mfma_f32_16x16x32_bf16 v[120:123], v[140:143], v[182:185], v[120:123]
	v_mfma_f32_16x16x32_bf16 v[116:119], v[132:135], v[190:193], v[116:119]
	v_mfma_f32_16x16x32_bf16 v[108:111], v[140:143], v[190:193], v[108:111]
	v_mfma_f32_16x16x32_bf16 v[96:99], v[132:135], v[198:201], v[96:99]
	v_mfma_f32_16x16x32_bf16 v[88:91], v[140:143], v[198:201], v[88:91]
	v_mfma_f32_16x16x32_bf16 v[84:87], v[132:135], v[206:209], v[84:87]
	v_mfma_f32_16x16x32_bf16 v[76:79], v[140:143], v[206:209], v[76:79]
	s_setprio 0
	s_setprio 1
	v_mfma_f32_16x16x32_bf16 v[112:115], v[156:159], v[178:181], v[112:115]
	v_mfma_f32_16x16x32_bf16 v[104:107], v[170:173], v[178:181], v[104:107]
	v_mfma_f32_16x16x32_bf16 v[100:103], v[156:159], v[186:189], v[100:103]
	v_mfma_f32_16x16x32_bf16 v[92:95], v[170:173], v[186:189], v[92:95]
	v_mfma_f32_16x16x32_bf16 v[80:83], v[156:159], v[194:197], v[80:83]
	v_mfma_f32_16x16x32_bf16 v[72:75], v[170:173], v[194:197], v[72:75]
	v_mfma_f32_16x16x32_bf16 v[68:71], v[156:159], v[202:205], v[68:71]
	v_mfma_f32_16x16x32_bf16 v[64:67], v[170:173], v[202:205], v[64:67]
	v_mfma_f32_16x16x32_bf16 v[112:115], v[166:169], v[182:185], v[112:115]
	v_mfma_f32_16x16x32_bf16 v[104:107], v[174:177], v[182:185], v[104:107]
	v_mfma_f32_16x16x32_bf16 v[100:103], v[166:169], v[190:193], v[100:103]
	v_mfma_f32_16x16x32_bf16 v[92:95], v[174:177], v[190:193], v[92:95]
	v_mfma_f32_16x16x32_bf16 v[80:83], v[166:169], v[198:201], v[80:83]
	v_mfma_f32_16x16x32_bf16 v[72:75], v[174:177], v[198:201], v[72:75]
	v_mfma_f32_16x16x32_bf16 v[68:71], v[166:169], v[206:209], v[68:71]
	v_mfma_f32_16x16x32_bf16 v[64:67], v[174:177], v[206:209], v[64:67]
	s_setprio 0
	s_barrier
	s_add_i32 s64, s55, s46
	v_lshl_add_u64 v[210:211], s[38:39], 0, v[144:145]
	s_mov_b32 m0, s64
	ds_read_b128 v[178:181], v165 offset:16384
	ds_read_b128 v[182:185], v165 offset:17408
	ds_read_b128 v[186:189], v165 offset:18432
	ds_read_b128 v[190:193], v165 offset:19456
	ds_read_b128 v[194:197], v165 offset:20480
	ds_read_b128 v[198:201], v165 offset:21504
	ds_read_b128 v[202:205], v165 offset:22528
	ds_read_b128 v[206:209], v165 offset:23552
	global_load_lds_dwordx4 v[210:211], off
	s_add_i32 m0, s64, 0x2000
	s_add_u32 s64, s38, 0x40000
	v_lshl_add_u64 v[212:213], s[38:39], 0, v[146:147]
	s_addc_u32 s65, s39, 0
	s_add_i32 s66, s56, s46
	global_load_lds_dwordx4 v[212:213], off
	v_lshl_add_u64 v[214:215], s[64:65], 0, v[144:145]
	s_mov_b32 m0, s66
	v_lshl_add_u64 v[216:217], s[40:41], 0, v[146:147]
	global_load_lds_dwordx4 v[214:215], off
	v_lshl_add_u64 v[214:215], s[64:65], 0, v[146:147]
	s_add_i32 m0, s66, 0x2000
	s_nop 0
	global_load_lds_dwordx4 v[214:215], off
	v_lshl_add_u64 v[214:215], s[40:41], 0, v[144:145]
	s_mov_b32 m0, s35
	s_nop 0
	global_load_lds_dwordx4 v[214:215], off
	s_mov_b32 m0, s47
	s_nop 0
	global_load_lds_dwordx4 v[216:217], off
	s_waitcnt vmcnt(8)
	s_waitcnt lgkmcnt(0)
	s_barrier
	s_setprio 1
	s_waitcnt lgkmcnt(0)
	v_mfma_f32_16x16x32_bf16 v[60:63], v[128:131], v[178:181], v[60:63]
	v_mfma_f32_16x16x32_bf16 v[56:59], v[136:139], v[178:181], v[56:59]
	v_mfma_f32_16x16x32_bf16 v[52:55], v[128:131], v[186:189], v[52:55]
	v_mfma_f32_16x16x32_bf16 v[44:47], v[136:139], v[186:189], v[44:47]
	v_mfma_f32_16x16x32_bf16 v[36:39], v[128:131], v[194:197], v[36:39]
	v_mfma_f32_16x16x32_bf16 v[28:31], v[136:139], v[194:197], v[28:31]
	v_mfma_f32_16x16x32_bf16 v[20:23], v[128:131], v[202:205], v[20:23]
	v_mfma_f32_16x16x32_bf16 v[12:15], v[136:139], v[202:205], v[12:15]
	v_mfma_f32_16x16x32_bf16 v[60:63], v[132:135], v[182:185], v[60:63]
	v_mfma_f32_16x16x32_bf16 v[56:59], v[140:143], v[182:185], v[56:59]
	v_mfma_f32_16x16x32_bf16 v[52:55], v[132:135], v[190:193], v[52:55]
	v_mfma_f32_16x16x32_bf16 v[44:47], v[140:143], v[190:193], v[44:47]
	v_mfma_f32_16x16x32_bf16 v[36:39], v[132:135], v[198:201], v[36:39]
	v_mfma_f32_16x16x32_bf16 v[28:31], v[140:143], v[198:201], v[28:31]
	v_mfma_f32_16x16x32_bf16 v[20:23], v[132:135], v[206:209], v[20:23]
	v_mfma_f32_16x16x32_bf16 v[12:15], v[140:143], v[206:209], v[12:15]
	s_setprio 0
	s_setprio 1
	v_mfma_f32_16x16x32_bf16 v[48:51], v[156:159], v[178:181], v[48:51]
	v_mfma_f32_16x16x32_bf16 v[40:43], v[170:173], v[178:181], v[40:43]
	v_mfma_f32_16x16x32_bf16 v[32:35], v[156:159], v[186:189], v[32:35]
	v_mfma_f32_16x16x32_bf16 v[24:27], v[170:173], v[186:189], v[24:27]
	v_mfma_f32_16x16x32_bf16 v[16:19], v[156:159], v[194:197], v[16:19]
	v_mfma_f32_16x16x32_bf16 v[8:11], v[170:173], v[194:197], v[8:11]
	v_mfma_f32_16x16x32_bf16 v[4:7], v[156:159], v[202:205], v[4:7]
	v_mfma_f32_16x16x32_bf16 v[0:3], v[170:173], v[202:205], v[0:3]
	v_mfma_f32_16x16x32_bf16 v[48:51], v[166:169], v[182:185], v[48:51]
	v_mfma_f32_16x16x32_bf16 v[40:43], v[174:177], v[182:185], v[40:43]
	v_mfma_f32_16x16x32_bf16 v[32:35], v[166:169], v[190:193], v[32:35]
	v_mfma_f32_16x16x32_bf16 v[24:27], v[174:177], v[190:193], v[24:27]
	v_mfma_f32_16x16x32_bf16 v[16:19], v[166:169], v[198:201], v[16:19]
	v_mfma_f32_16x16x32_bf16 v[8:11], v[174:177], v[198:201], v[8:11]
	v_mfma_f32_16x16x32_bf16 v[4:7], v[166:169], v[206:209], v[4:7]
	v_mfma_f32_16x16x32_bf16 v[0:3], v[174:177], v[206:209], v[0:3]
	s_setprio 0
	s_barrier
	s_add_i32 s64, 0, 0x18000
	s_add_i32 s65, 0, 0x1c000
	v_add_u32_e32 v140, s64, v161
	v_add_u32_e32 v174, s65, v161
	ds_read_b128 v[128:131], v140
	ds_read_b128 v[132:135], v140 offset:1024
	ds_read_b128 v[136:139], v140 offset:2048
	ds_read_b128 v[140:143], v140 offset:3072
	ds_read_b128 v[156:159], v174
	ds_read_b128 v[166:169], v174 offset:1024
	ds_read_b128 v[170:173], v174 offset:2048
	ds_read_b128 v[174:177], v174 offset:3072
	s_add_u32 s40, s40, 0x40000
	s_addc_u32 s41, s41, 0
	s_mov_b32 m0, s48
	v_lshl_add_u64 v[218:219], s[40:41], 0, v[144:145]
	ds_read_b128 v[178:181], v165 offset:32768
	ds_read_b128 v[182:185], v165 offset:33792
	ds_read_b128 v[186:189], v165 offset:34816
	ds_read_b128 v[190:193], v165 offset:35840
	ds_read_b128 v[194:197], v165 offset:36864
	ds_read_b128 v[198:201], v165 offset:37888
	ds_read_b128 v[202:205], v165 offset:38912
	ds_read_b128 v[206:209], v165 offset:39936
	global_load_lds_dwordx4 v[218:219], off
	v_lshl_add_u64 v[218:219], s[40:41], 0, v[146:147]
	s_mov_b32 m0, s49
	s_nop 0
	global_load_lds_dwordx4 v[218:219], off
	s_waitcnt vmcnt(8)
	s_waitcnt lgkmcnt(0)
	s_barrier
	s_setprio 1
	s_waitcnt lgkmcnt(0)
	v_mfma_f32_16x16x32_bf16 v[124:127], v[128:131], v[178:181], v[124:127]
	v_mfma_f32_16x16x32_bf16 v[120:123], v[136:139], v[178:181], v[120:123]
	v_mfma_f32_16x16x32_bf16 v[116:119], v[128:131], v[186:189], v[116:119]
	v_mfma_f32_16x16x32_bf16 v[108:111], v[136:139], v[186:189], v[108:111]
	v_mfma_f32_16x16x32_bf16 v[96:99], v[128:131], v[194:197], v[96:99]
	v_mfma_f32_16x16x32_bf16 v[88:91], v[136:139], v[194:197], v[88:91]
	v_mfma_f32_16x16x32_bf16 v[84:87], v[128:131], v[202:205], v[84:87]
	v_mfma_f32_16x16x32_bf16 v[76:79], v[136:139], v[202:205], v[76:79]
	v_mfma_f32_16x16x32_bf16 v[124:127], v[132:135], v[182:185], v[124:127]
	v_mfma_f32_16x16x32_bf16 v[120:123], v[140:143], v[182:185], v[120:123]
	v_mfma_f32_16x16x32_bf16 v[116:119], v[132:135], v[190:193], v[116:119]
	v_mfma_f32_16x16x32_bf16 v[108:111], v[140:143], v[190:193], v[108:111]
	v_mfma_f32_16x16x32_bf16 v[96:99], v[132:135], v[198:201], v[96:99]
	v_mfma_f32_16x16x32_bf16 v[88:91], v[140:143], v[198:201], v[88:91]
	v_mfma_f32_16x16x32_bf16 v[84:87], v[132:135], v[206:209], v[84:87]
	v_mfma_f32_16x16x32_bf16 v[76:79], v[140:143], v[206:209], v[76:79]
	s_setprio 0
	s_setprio 1
	v_mfma_f32_16x16x32_bf16 v[112:115], v[156:159], v[178:181], v[112:115]
	v_mfma_f32_16x16x32_bf16 v[104:107], v[170:173], v[178:181], v[104:107]
	v_mfma_f32_16x16x32_bf16 v[100:103], v[156:159], v[186:189], v[100:103]
	v_mfma_f32_16x16x32_bf16 v[92:95], v[170:173], v[186:189], v[92:95]
	v_mfma_f32_16x16x32_bf16 v[80:83], v[156:159], v[194:197], v[80:83]
	v_mfma_f32_16x16x32_bf16 v[72:75], v[170:173], v[194:197], v[72:75]
	v_mfma_f32_16x16x32_bf16 v[68:71], v[156:159], v[202:205], v[68:71]
	v_mfma_f32_16x16x32_bf16 v[64:67], v[170:173], v[202:205], v[64:67]
	v_mfma_f32_16x16x32_bf16 v[112:115], v[166:169], v[182:185], v[112:115]
	v_mfma_f32_16x16x32_bf16 v[104:107], v[174:177], v[182:185], v[104:107]
	v_mfma_f32_16x16x32_bf16 v[100:103], v[166:169], v[190:193], v[100:103]
	v_mfma_f32_16x16x32_bf16 v[92:95], v[174:177], v[190:193], v[92:95]
	v_mfma_f32_16x16x32_bf16 v[80:83], v[166:169], v[198:201], v[80:83]
	v_mfma_f32_16x16x32_bf16 v[72:75], v[174:177], v[198:201], v[72:75]
	v_mfma_f32_16x16x32_bf16 v[68:71], v[166:169], v[206:209], v[68:71]
	v_mfma_f32_16x16x32_bf16 v[64:67], v[174:177], v[206:209], v[64:67]
	s_setprio 0
	s_barrier
	s_add_i32 s40, s64, s46
	v_lshl_add_u64 v[210:211], v[210:211], 0, s[8:9]
	s_mov_b32 m0, s40
	ds_read_b128 v[178:181], v165 offset:49152
	ds_read_b128 v[182:185], v165 offset:50176
	ds_read_b128 v[186:189], v165 offset:51200
	ds_read_b128 v[190:193], v165 offset:52224
	ds_read_b128 v[194:197], v165 offset:53248
	ds_read_b128 v[198:201], v165 offset:54272
	ds_read_b128 v[202:205], v165 offset:55296
	ds_read_b128 v[206:209], v165 offset:56320
	global_load_lds_dwordx4 v[210:211], off
	s_add_i32 m0, s40, 0x2000
	s_add_u32 s38, s38, 0x40080
	v_lshl_add_u64 v[210:211], v[212:213], 0, s[8:9]
	s_addc_u32 s39, s39, 0
	s_add_i32 s40, s65, s46
	global_load_lds_dwordx4 v[210:211], off
	v_lshl_add_u64 v[210:211], s[38:39], 0, v[144:145]
	s_mov_b32 m0, s40
	s_nop 0
	global_load_lds_dwordx4 v[210:211], off
	v_lshl_add_u64 v[210:211], s[38:39], 0, v[146:147]
	s_add_i32 m0, s40, 0x2000
	s_nop 0
	global_load_lds_dwordx4 v[210:211], off
	v_lshl_add_u64 v[210:211], v[214:215], 0, s[8:9]
	s_mov_b32 m0, s52
	s_nop 0
	global_load_lds_dwordx4 v[210:211], off
	v_lshl_add_u64 v[210:211], v[216:217], 0, s[8:9]
	s_mov_b32 m0, s53
	s_nop 0
	global_load_lds_dwordx4 v[210:211], off
	s_waitcnt vmcnt(8)
	s_waitcnt lgkmcnt(0)
	s_barrier
	s_setprio 1
	s_waitcnt lgkmcnt(0)
	v_mfma_f32_16x16x32_bf16 v[60:63], v[128:131], v[178:181], v[60:63]
	v_mfma_f32_16x16x32_bf16 v[56:59], v[136:139], v[178:181], v[56:59]
	v_mfma_f32_16x16x32_bf16 v[52:55], v[128:131], v[186:189], v[52:55]
	v_mfma_f32_16x16x32_bf16 v[44:47], v[136:139], v[186:189], v[44:47]
	v_mfma_f32_16x16x32_bf16 v[36:39], v[128:131], v[194:197], v[36:39]
	v_mfma_f32_16x16x32_bf16 v[28:31], v[136:139], v[194:197], v[28:31]
	v_mfma_f32_16x16x32_bf16 v[20:23], v[128:131], v[202:205], v[20:23]
	v_mfma_f32_16x16x32_bf16 v[12:15], v[136:139], v[202:205], v[12:15]
	v_mfma_f32_16x16x32_bf16 v[60:63], v[132:135], v[182:185], v[60:63]
	v_mfma_f32_16x16x32_bf16 v[56:59], v[140:143], v[182:185], v[56:59]
	v_mfma_f32_16x16x32_bf16 v[52:55], v[132:135], v[190:193], v[52:55]
	v_mfma_f32_16x16x32_bf16 v[44:47], v[140:143], v[190:193], v[44:47]
	v_mfma_f32_16x16x32_bf16 v[36:39], v[132:135], v[198:201], v[36:39]
	v_mfma_f32_16x16x32_bf16 v[28:31], v[140:143], v[198:201], v[28:31]
	v_mfma_f32_16x16x32_bf16 v[20:23], v[132:135], v[206:209], v[20:23]
	v_mfma_f32_16x16x32_bf16 v[12:15], v[140:143], v[206:209], v[12:15]
	s_setprio 0
	s_setprio 1
	v_mfma_f32_16x16x32_bf16 v[48:51], v[156:159], v[178:181], v[48:51]
	v_mfma_f32_16x16x32_bf16 v[40:43], v[170:173], v[178:181], v[40:43]
	v_mfma_f32_16x16x32_bf16 v[32:35], v[156:159], v[186:189], v[32:35]
	v_mfma_f32_16x16x32_bf16 v[24:27], v[170:173], v[186:189], v[24:27]
	v_mfma_f32_16x16x32_bf16 v[16:19], v[156:159], v[194:197], v[16:19]
	s_add_i32 s63, s63, 2
	v_mfma_f32_16x16x32_bf16 v[8:11], v[170:173], v[194:197], v[8:11]
	v_mfma_f32_16x16x32_bf16 v[4:7], v[156:159], v[202:205], v[4:7]
	s_add_u32 s36, s36, 0x100
	s_addc_u32 s37, s37, 0
	v_mfma_f32_16x16x32_bf16 v[0:3], v[170:173], v[202:205], v[0:3]
	v_mfma_f32_16x16x32_bf16 v[48:51], v[166:169], v[182:185], v[48:51]
	s_add_u32 s61, s61, 0x100
	s_addc_u32 s62, s62, 0
	v_mfma_f32_16x16x32_bf16 v[40:43], v[174:177], v[182:185], v[40:43]
	v_mfma_f32_16x16x32_bf16 v[32:35], v[166:169], v[190:193], v[32:35]
	s_cmp_gt_u32 s63, 13
	v_mfma_f32_16x16x32_bf16 v[24:27], v[174:177], v[190:193], v[24:27]
	v_mfma_f32_16x16x32_bf16 v[16:19], v[166:169], v[198:201], v[16:19]
	v_mfma_f32_16x16x32_bf16 v[8:11], v[174:177], v[198:201], v[8:11]
	v_mfma_f32_16x16x32_bf16 v[4:7], v[166:169], v[206:209], v[4:7]
	v_mfma_f32_16x16x32_bf16 v[0:3], v[174:177], v[206:209], v[0:3]
	s_setprio 0
	s_barrier
	s_cbranch_scc0 .LBB0_766
	s_and_b64 vcc, exec, s[12:13]
	s_cbranch_vccz .LBB0_769
	s_barrier
